# weight transposer gain path: one coalesced gain load + v_readlane broadcasts instead of four serial vmcnt(0)-drained groups of dwordx4 gain loads per tile
# speedup vs baseline: 1.0043x; 1.0043x over previous
.LBB0_85:
	s_cmp_eq_u64 s[52:53], 0
	s_cbranch_scc1 .LBB0_87
	s_mov_b32 s51, s37
	s_lshl_b64 s[56:57], s[50:51], 2
	s_add_u32 s52, s52, s56
	s_addc_u32 s53, s53, s57
	s_mov_b64 s[100:101], exec
	s_mov_b64 exec, -1
	v_mbcnt_lo_u32_b32 v0, -1, 0
	v_mbcnt_hi_u32_b32 v0, -1, v0
	v_lshlrev_b32_e32 v0, 2, v0
	global_load_dword v0, v0, s[52:53]
	s_mov_b64 exec, s[100:101]
	s_waitcnt vmcnt(0)
	v_readlane_b32 s100, v0, 12
	v_readlane_b32 s101, v0, 13
	s_nop 1
	v_pk_mul_f32 v[96:97], v[96:97], s[100:101]
	v_readlane_b32 s100, v0, 8
	v_readlane_b32 s101, v0, 9
	s_nop 1
	v_pk_mul_f32 v[92:93], v[92:93], s[100:101]
	v_readlane_b32 s100, v0, 4
	v_readlane_b32 s101, v0, 5
	s_nop 1
	v_pk_mul_f32 v[88:89], v[88:89], s[100:101]
	v_readlane_b32 s100, v0, 0
	v_readlane_b32 s101, v0, 1
	s_nop 1
	v_pk_mul_f32 v[84:85], v[84:85], s[100:101]
	v_readlane_b32 s100, v0, 2
	v_readlane_b32 s101, v0, 3
	s_nop 1
	v_pk_mul_f32 v[86:87], v[86:87], s[100:101]
	v_readlane_b32 s100, v0, 6
	v_readlane_b32 s101, v0, 7
	s_nop 1
	v_pk_mul_f32 v[90:91], v[90:91], s[100:101]
	v_readlane_b32 s100, v0, 10
	v_readlane_b32 s101, v0, 11
	s_nop 1
	v_pk_mul_f32 v[94:95], v[94:95], s[100:101]
	v_readlane_b32 s100, v0, 14
	v_readlane_b32 s101, v0, 15
	s_nop 1
	v_pk_mul_f32 v[98:99], v[98:99], s[100:101]
	v_readlane_b32 s100, v0, 28
	v_readlane_b32 s101, v0, 29
	s_nop 1
	v_pk_mul_f32 v[112:113], v[112:113], s[100:101]
	v_readlane_b32 s100, v0, 24
	v_readlane_b32 s101, v0, 25
	s_nop 1
	v_pk_mul_f32 v[108:109], v[108:109], s[100:101]
	v_readlane_b32 s100, v0, 20
	v_readlane_b32 s101, v0, 21
	s_nop 1
	v_pk_mul_f32 v[104:105], v[104:105], s[100:101]
	v_readlane_b32 s100, v0, 16
	v_readlane_b32 s101, v0, 17
	s_nop 1
	v_pk_mul_f32 v[100:101], v[100:101], s[100:101]
	v_readlane_b32 s100, v0, 18
	v_readlane_b32 s101, v0, 19
	s_nop 1
	v_pk_mul_f32 v[102:103], v[102:103], s[100:101]
	v_readlane_b32 s100, v0, 22
	v_readlane_b32 s101, v0, 23
	s_nop 1
	v_pk_mul_f32 v[106:107], v[106:107], s[100:101]
	v_readlane_b32 s100, v0, 26
	v_readlane_b32 s101, v0, 27
	s_nop 1
	v_pk_mul_f32 v[110:111], v[110:111], s[100:101]
	v_readlane_b32 s100, v0, 30
	v_readlane_b32 s101, v0, 31
	s_nop 1
	v_pk_mul_f32 v[114:115], v[114:115], s[100:101]
	v_readlane_b32 s100, v0, 44
	v_readlane_b32 s101, v0, 45
	s_nop 1
	v_pk_mul_f32 v[138:139], v[138:139], s[100:101]
	v_readlane_b32 s100, v0, 40
	v_readlane_b32 s101, v0, 41
	s_nop 1
	v_pk_mul_f32 v[130:131], v[130:131], s[100:101]
	v_readlane_b32 s100, v0, 36
	v_readlane_b32 s101, v0, 37
	s_nop 1
	v_pk_mul_f32 v[120:121], v[120:121], s[100:101]
	v_readlane_b32 s100, v0, 32
	v_readlane_b32 s101, v0, 33
	s_nop 1
	v_pk_mul_f32 v[116:117], v[116:117], s[100:101]
	v_readlane_b32 s100, v0, 34
	v_readlane_b32 s101, v0, 35
	s_nop 1
	v_pk_mul_f32 v[118:119], v[118:119], s[100:101]
	v_readlane_b32 s100, v0, 38
	v_readlane_b32 s101, v0, 39
	s_nop 1
	v_pk_mul_f32 v[126:127], v[126:127], s[100:101]
	v_readlane_b32 s100, v0, 42
	v_readlane_b32 s101, v0, 43
	s_nop 1
	v_pk_mul_f32 v[134:135], v[134:135], s[100:101]
	v_readlane_b32 s100, v0, 46
	v_readlane_b32 s101, v0, 47
	s_nop 1
	v_pk_mul_f32 v[142:143], v[142:143], s[100:101]
	v_readlane_b32 s100, v0, 60
	v_readlane_b32 s101, v0, 61
	s_nop 1
	v_pk_mul_f32 v[144:145], v[144:145], s[100:101]
	v_readlane_b32 s100, v0, 56
	v_readlane_b32 s101, v0, 57
	s_nop 1
	v_pk_mul_f32 v[136:137], v[136:137], s[100:101]
	v_readlane_b32 s100, v0, 52
	v_readlane_b32 s101, v0, 53
	s_nop 1
	v_pk_mul_f32 v[128:129], v[128:129], s[100:101]
	v_readlane_b32 s100, v0, 48
	v_readlane_b32 s101, v0, 49
	s_nop 1
	v_pk_mul_f32 v[124:125], v[124:125], s[100:101]
	v_readlane_b32 s100, v0, 50
	v_readlane_b32 s101, v0, 51
	s_nop 1
	v_pk_mul_f32 v[122:123], v[122:123], s[100:101]
	v_readlane_b32 s100, v0, 54
	v_readlane_b32 s101, v0, 55
	s_nop 1
	v_pk_mul_f32 v[132:133], v[132:133], s[100:101]
	v_readlane_b32 s100, v0, 58
	v_readlane_b32 s101, v0, 59
	s_nop 1
	v_pk_mul_f32 v[140:141], v[140:141], s[100:101]
	v_readlane_b32 s100, v0, 62
	v_readlane_b32 s101, v0, 63
	s_nop 1
	v_pk_mul_f32 v[146:147], v[146:147], s[100:101]

.LBB0_215:
	s_cmp_eq_u64 s[70:71], 0
	s_cbranch_scc1 .LBB0_217
	s_mov_b32 s69, s41
	s_lshl_b64 s[18:19], s[68:69], 2
	s_add_u32 s70, s70, s18
	s_addc_u32 s71, s71, s19
	s_mov_b64 s[100:101], exec
	s_mov_b64 exec, -1
	v_mbcnt_lo_u32_b32 v182, -1, 0
	v_mbcnt_hi_u32_b32 v182, -1, v182
	v_lshlrev_b32_e32 v182, 2, v182
	global_load_dword v182, v182, s[70:71]
	s_mov_b64 exec, s[100:101]
	s_waitcnt vmcnt(0)
	v_readlane_b32 s100, v182, 12
	v_readlane_b32 s101, v182, 13
	s_nop 1
	v_pk_mul_f32 v[84:85], v[84:85], s[100:101]
	v_readlane_b32 s100, v182, 8
	v_readlane_b32 s101, v182, 9
	s_nop 1
	v_pk_mul_f32 v[80:81], v[80:81], s[100:101]
	v_readlane_b32 s100, v182, 4
	v_readlane_b32 s101, v182, 5
	s_nop 1
	v_pk_mul_f32 v[76:77], v[76:77], s[100:101]
	v_readlane_b32 s100, v182, 0
	v_readlane_b32 s101, v182, 1
	s_nop 1
	v_pk_mul_f32 v[72:73], v[72:73], s[100:101]
	v_readlane_b32 s100, v182, 2
	v_readlane_b32 s101, v182, 3
	s_nop 1
	v_pk_mul_f32 v[74:75], v[74:75], s[100:101]
	v_readlane_b32 s100, v182, 6
	v_readlane_b32 s101, v182, 7
	s_nop 1
	v_pk_mul_f32 v[78:79], v[78:79], s[100:101]
	v_readlane_b32 s100, v182, 10
	v_readlane_b32 s101, v182, 11
	s_nop 1
	v_pk_mul_f32 v[82:83], v[82:83], s[100:101]
	v_readlane_b32 s100, v182, 14
	v_readlane_b32 s101, v182, 15
	s_nop 1
	v_pk_mul_f32 v[86:87], v[86:87], s[100:101]
	v_readlane_b32 s100, v182, 28
	v_readlane_b32 s101, v182, 29
	s_nop 1
	v_pk_mul_f32 v[100:101], v[100:101], s[100:101]
	v_readlane_b32 s100, v182, 24
	v_readlane_b32 s101, v182, 25
	s_nop 1
	v_pk_mul_f32 v[96:97], v[96:97], s[100:101]
	v_readlane_b32 s100, v182, 20
	v_readlane_b32 s101, v182, 21
	s_nop 1
	v_pk_mul_f32 v[92:93], v[92:93], s[100:101]
	v_readlane_b32 s100, v182, 16
	v_readlane_b32 s101, v182, 17
	s_nop 1
	v_pk_mul_f32 v[88:89], v[88:89], s[100:101]
	v_readlane_b32 s100, v182, 18
	v_readlane_b32 s101, v182, 19
	s_nop 1
	v_pk_mul_f32 v[90:91], v[90:91], s[100:101]
	v_readlane_b32 s100, v182, 22
	v_readlane_b32 s101, v182, 23
	s_nop 1
	v_pk_mul_f32 v[94:95], v[94:95], s[100:101]
	v_readlane_b32 s100, v182, 26
	v_readlane_b32 s101, v182, 27
	s_nop 1
	v_pk_mul_f32 v[98:99], v[98:99], s[100:101]
	v_readlane_b32 s100, v182, 30
	v_readlane_b32 s101, v182, 31
	s_nop 1
	v_pk_mul_f32 v[102:103], v[102:103], s[100:101]
	v_readlane_b32 s100, v182, 44
	v_readlane_b32 s101, v182, 45
	s_nop 1
	v_pk_mul_f32 v[116:117], v[116:117], s[100:101]
	v_readlane_b32 s100, v182, 40
	v_readlane_b32 s101, v182, 41
	s_nop 1
	v_pk_mul_f32 v[112:113], v[112:113], s[100:101]
	v_readlane_b32 s100, v182, 36
	v_readlane_b32 s101, v182, 37
	s_nop 1
	v_pk_mul_f32 v[108:109], v[108:109], s[100:101]
	v_readlane_b32 s100, v182, 32
	v_readlane_b32 s101, v182, 33
	s_nop 1
	v_pk_mul_f32 v[104:105], v[104:105], s[100:101]
	v_readlane_b32 s100, v182, 34
	v_readlane_b32 s101, v182, 35
	s_nop 1
	v_pk_mul_f32 v[106:107], v[106:107], s[100:101]
	v_readlane_b32 s100, v182, 38
	v_readlane_b32 s101, v182, 39
	s_nop 1
	v_pk_mul_f32 v[110:111], v[110:111], s[100:101]
	v_readlane_b32 s100, v182, 42
	v_readlane_b32 s101, v182, 43
	s_nop 1
	v_pk_mul_f32 v[114:115], v[114:115], s[100:101]
	v_readlane_b32 s100, v182, 46
	v_readlane_b32 s101, v182, 47
	s_nop 1
	v_pk_mul_f32 v[118:119], v[118:119], s[100:101]
	v_readlane_b32 s100, v182, 60
	v_readlane_b32 s101, v182, 61
	s_nop 1
	v_pk_mul_f32 v[132:133], v[132:133], s[100:101]
	v_readlane_b32 s100, v182, 56
	v_readlane_b32 s101, v182, 57
	s_nop 1
	v_pk_mul_f32 v[128:129], v[128:129], s[100:101]
	v_readlane_b32 s100, v182, 52
	v_readlane_b32 s101, v182, 53
	s_nop 1
	v_pk_mul_f32 v[124:125], v[124:125], s[100:101]
	v_readlane_b32 s100, v182, 48
	v_readlane_b32 s101, v182, 49
	s_nop 1
	v_pk_mul_f32 v[120:121], v[120:121], s[100:101]
	v_readlane_b32 s100, v182, 50
	v_readlane_b32 s101, v182, 51
	s_nop 1
	v_pk_mul_f32 v[122:123], v[122:123], s[100:101]
	v_readlane_b32 s100, v182, 54
	v_readlane_b32 s101, v182, 55
	s_nop 1
	v_pk_mul_f32 v[126:127], v[126:127], s[100:101]
	v_readlane_b32 s100, v182, 58
	v_readlane_b32 s101, v182, 59
	s_nop 1
	v_pk_mul_f32 v[130:131], v[130:131], s[100:101]
	v_readlane_b32 s100, v182, 62
	v_readlane_b32 s101, v182, 63
	s_nop 1
	v_pk_mul_f32 v[134:135], v[134:135], s[100:101]

.LBB0_302:
	s_cmp_eq_u64 s[70:71], 0
	s_cbranch_scc1 .LBB0_304
	s_mov_b32 s79, s41
	s_lshl_b64 s[22:23], s[78:79], 2
	s_add_u32 s70, s70, s22
	s_addc_u32 s71, s71, s23
	s_mov_b64 s[100:101], exec
	s_mov_b64 exec, -1
	v_mbcnt_lo_u32_b32 v0, -1, 0
	v_mbcnt_hi_u32_b32 v0, -1, v0
	v_lshlrev_b32_e32 v0, 2, v0
	global_load_dword v0, v0, s[70:71]
	s_mov_b64 exec, s[100:101]
	s_waitcnt vmcnt(0)
	v_readlane_b32 s100, v0, 12
	v_readlane_b32 s101, v0, 13
	s_nop 1
	v_pk_mul_f32 v[92:93], v[92:93], s[100:101]
	v_readlane_b32 s100, v0, 8
	v_readlane_b32 s101, v0, 9
	s_nop 1
	v_pk_mul_f32 v[88:89], v[88:89], s[100:101]
	v_readlane_b32 s100, v0, 4
	v_readlane_b32 s101, v0, 5
	s_nop 1
	v_pk_mul_f32 v[84:85], v[84:85], s[100:101]
	v_readlane_b32 s100, v0, 0
	v_readlane_b32 s101, v0, 1
	s_nop 1
	v_pk_mul_f32 v[80:81], v[80:81], s[100:101]
	v_readlane_b32 s100, v0, 2
	v_readlane_b32 s101, v0, 3
	s_nop 1
	v_pk_mul_f32 v[82:83], v[82:83], s[100:101]
	v_readlane_b32 s100, v0, 6
	v_readlane_b32 s101, v0, 7
	s_nop 1
	v_pk_mul_f32 v[86:87], v[86:87], s[100:101]
	v_readlane_b32 s100, v0, 10
	v_readlane_b32 s101, v0, 11
	s_nop 1
	v_pk_mul_f32 v[90:91], v[90:91], s[100:101]
	v_readlane_b32 s100, v0, 14
	v_readlane_b32 s101, v0, 15
	s_nop 1
	v_pk_mul_f32 v[94:95], v[94:95], s[100:101]
	v_readlane_b32 s100, v0, 28
	v_readlane_b32 s101, v0, 29
	s_nop 1
	v_pk_mul_f32 v[108:109], v[108:109], s[100:101]
	v_readlane_b32 s100, v0, 24
	v_readlane_b32 s101, v0, 25
	s_nop 1
	v_pk_mul_f32 v[104:105], v[104:105], s[100:101]
	v_readlane_b32 s100, v0, 20
	v_readlane_b32 s101, v0, 21
	s_nop 1
	v_pk_mul_f32 v[100:101], v[100:101], s[100:101]
	v_readlane_b32 s100, v0, 16
	v_readlane_b32 s101, v0, 17
	s_nop 1
	v_pk_mul_f32 v[96:97], v[96:97], s[100:101]
	v_readlane_b32 s100, v0, 18
	v_readlane_b32 s101, v0, 19
	s_nop 1
	v_pk_mul_f32 v[98:99], v[98:99], s[100:101]
	v_readlane_b32 s100, v0, 22
	v_readlane_b32 s101, v0, 23
	s_nop 1
	v_pk_mul_f32 v[102:103], v[102:103], s[100:101]
	v_readlane_b32 s100, v0, 26
	v_readlane_b32 s101, v0, 27
	s_nop 1
	v_pk_mul_f32 v[106:107], v[106:107], s[100:101]
	v_readlane_b32 s100, v0, 30
	v_readlane_b32 s101, v0, 31
	s_nop 1
	v_pk_mul_f32 v[110:111], v[110:111], s[100:101]
	v_readlane_b32 s100, v0, 44
	v_readlane_b32 s101, v0, 45
	s_nop 1
	v_pk_mul_f32 v[124:125], v[124:125], s[100:101]
	v_readlane_b32 s100, v0, 40
	v_readlane_b32 s101, v0, 41
	s_nop 1
	v_pk_mul_f32 v[120:121], v[120:121], s[100:101]
	v_readlane_b32 s100, v0, 36
	v_readlane_b32 s101, v0, 37
	s_nop 1
	v_pk_mul_f32 v[116:117], v[116:117], s[100:101]
	v_readlane_b32 s100, v0, 32
	v_readlane_b32 s101, v0, 33
	s_nop 1
	v_pk_mul_f32 v[112:113], v[112:113], s[100:101]
	v_readlane_b32 s100, v0, 34
	v_readlane_b32 s101, v0, 35
	s_nop 1
	v_pk_mul_f32 v[114:115], v[114:115], s[100:101]
	v_readlane_b32 s100, v0, 38
	v_readlane_b32 s101, v0, 39
	s_nop 1
	v_pk_mul_f32 v[118:119], v[118:119], s[100:101]
	v_readlane_b32 s100, v0, 42
	v_readlane_b32 s101, v0, 43
	s_nop 1
	v_pk_mul_f32 v[122:123], v[122:123], s[100:101]
	v_readlane_b32 s100, v0, 46
	v_readlane_b32 s101, v0, 47
	s_nop 1
	v_pk_mul_f32 v[126:127], v[126:127], s[100:101]
	v_readlane_b32 s100, v0, 60
	v_readlane_b32 s101, v0, 61
	s_nop 1
	v_pk_mul_f32 v[140:141], v[140:141], s[100:101]
	v_readlane_b32 s100, v0, 56
	v_readlane_b32 s101, v0, 57
	s_nop 1
	v_pk_mul_f32 v[136:137], v[136:137], s[100:101]
	v_readlane_b32 s100, v0, 52
	v_readlane_b32 s101, v0, 53
	s_nop 1
	v_pk_mul_f32 v[132:133], v[132:133], s[100:101]
	v_readlane_b32 s100, v0, 48
	v_readlane_b32 s101, v0, 49
	s_nop 1
	v_pk_mul_f32 v[128:129], v[128:129], s[100:101]
	v_readlane_b32 s100, v0, 50
	v_readlane_b32 s101, v0, 51
	s_nop 1
	v_pk_mul_f32 v[130:131], v[130:131], s[100:101]
	v_readlane_b32 s100, v0, 54
	v_readlane_b32 s101, v0, 55
	s_nop 1
	v_pk_mul_f32 v[134:135], v[134:135], s[100:101]
	v_readlane_b32 s100, v0, 58
	v_readlane_b32 s101, v0, 59
	s_nop 1
	v_pk_mul_f32 v[138:139], v[138:139], s[100:101]
	v_readlane_b32 s100, v0, 62
	v_readlane_b32 s101, v0, 63
	s_nop 1
	v_pk_mul_f32 v[142:143], v[142:143], s[100:101]

.LBB0_756:
	s_cmp_eq_u64 s[70:71], 0
	s_cbranch_scc1 .LBB0_758
	s_mov_b32 s85, s41
	s_lshl_b64 s[46:47], s[84:85], 2
	s_add_u32 s70, s70, s46
	s_addc_u32 s71, s71, s47
	s_mov_b64 s[100:101], exec
	s_mov_b64 exec, -1
	v_mbcnt_lo_u32_b32 v0, -1, 0
	v_mbcnt_hi_u32_b32 v0, -1, v0
	v_lshlrev_b32_e32 v0, 2, v0
	global_load_dword v0, v0, s[70:71]
	s_mov_b64 exec, s[100:101]
	s_waitcnt vmcnt(0)
	v_readlane_b32 s100, v0, 12
	v_readlane_b32 s101, v0, 13
	s_nop 1
	v_pk_mul_f32 v[94:95], v[94:95], s[100:101]
	v_readlane_b32 s100, v0, 8
	v_readlane_b32 s101, v0, 9
	s_nop 1
	v_pk_mul_f32 v[90:91], v[90:91], s[100:101]
	v_readlane_b32 s100, v0, 4
	v_readlane_b32 s101, v0, 5
	s_nop 1
	v_pk_mul_f32 v[86:87], v[86:87], s[100:101]
	v_readlane_b32 s100, v0, 0
	v_readlane_b32 s101, v0, 1
	s_nop 1
	v_pk_mul_f32 v[82:83], v[82:83], s[100:101]
	v_readlane_b32 s100, v0, 2
	v_readlane_b32 s101, v0, 3
	s_nop 1
	v_pk_mul_f32 v[84:85], v[84:85], s[100:101]
	v_readlane_b32 s100, v0, 6
	v_readlane_b32 s101, v0, 7
	s_nop 1
	v_pk_mul_f32 v[88:89], v[88:89], s[100:101]
	v_readlane_b32 s100, v0, 10
	v_readlane_b32 s101, v0, 11
	s_nop 1
	v_pk_mul_f32 v[92:93], v[92:93], s[100:101]
	v_readlane_b32 s100, v0, 14
	v_readlane_b32 s101, v0, 15
	s_nop 1
	v_pk_mul_f32 v[96:97], v[96:97], s[100:101]
	v_readlane_b32 s100, v0, 28
	v_readlane_b32 s101, v0, 29
	s_nop 1
	v_pk_mul_f32 v[110:111], v[110:111], s[100:101]
	v_readlane_b32 s100, v0, 24
	v_readlane_b32 s101, v0, 25
	s_nop 1
	v_pk_mul_f32 v[106:107], v[106:107], s[100:101]
	v_readlane_b32 s100, v0, 20
	v_readlane_b32 s101, v0, 21
	s_nop 1
	v_pk_mul_f32 v[102:103], v[102:103], s[100:101]
	v_readlane_b32 s100, v0, 16
	v_readlane_b32 s101, v0, 17
	s_nop 1
	v_pk_mul_f32 v[98:99], v[98:99], s[100:101]
	v_readlane_b32 s100, v0, 18
	v_readlane_b32 s101, v0, 19
	s_nop 1
	v_pk_mul_f32 v[100:101], v[100:101], s[100:101]
	v_readlane_b32 s100, v0, 22
	v_readlane_b32 s101, v0, 23
	s_nop 1
	v_pk_mul_f32 v[104:105], v[104:105], s[100:101]
	v_readlane_b32 s100, v0, 26
	v_readlane_b32 s101, v0, 27
	s_nop 1
	v_pk_mul_f32 v[108:109], v[108:109], s[100:101]
	v_readlane_b32 s100, v0, 30
	v_readlane_b32 s101, v0, 31
	s_nop 1
	v_pk_mul_f32 v[112:113], v[112:113], s[100:101]
	v_readlane_b32 s100, v0, 44
	v_readlane_b32 s101, v0, 45
	s_nop 1
	v_pk_mul_f32 v[126:127], v[126:127], s[100:101]
	v_readlane_b32 s100, v0, 40
	v_readlane_b32 s101, v0, 41
	s_nop 1
	v_pk_mul_f32 v[122:123], v[122:123], s[100:101]
	v_readlane_b32 s100, v0, 36
	v_readlane_b32 s101, v0, 37
	s_nop 1
	v_pk_mul_f32 v[118:119], v[118:119], s[100:101]
	v_readlane_b32 s100, v0, 32
	v_readlane_b32 s101, v0, 33
	s_nop 1
	v_pk_mul_f32 v[114:115], v[114:115], s[100:101]
	v_readlane_b32 s100, v0, 34
	v_readlane_b32 s101, v0, 35
	s_nop 1
	v_pk_mul_f32 v[116:117], v[116:117], s[100:101]
	v_readlane_b32 s100, v0, 38
	v_readlane_b32 s101, v0, 39
	s_nop 1
	v_pk_mul_f32 v[120:121], v[120:121], s[100:101]
	v_readlane_b32 s100, v0, 42
	v_readlane_b32 s101, v0, 43
	s_nop 1
	v_pk_mul_f32 v[124:125], v[124:125], s[100:101]
	v_readlane_b32 s100, v0, 46
	v_readlane_b32 s101, v0, 47
	s_nop 1
	v_pk_mul_f32 v[128:129], v[128:129], s[100:101]
	v_readlane_b32 s100, v0, 60
	v_readlane_b32 s101, v0, 61
	s_nop 1
	v_pk_mul_f32 v[142:143], v[142:143], s[100:101]
	v_readlane_b32 s100, v0, 56
	v_readlane_b32 s101, v0, 57
	s_nop 1
	v_pk_mul_f32 v[138:139], v[138:139], s[100:101]
	v_readlane_b32 s100, v0, 52
	v_readlane_b32 s101, v0, 53
	s_nop 1
	v_pk_mul_f32 v[134:135], v[134:135], s[100:101]
	v_readlane_b32 s100, v0, 48
	v_readlane_b32 s101, v0, 49
	s_nop 1
	v_pk_mul_f32 v[130:131], v[130:131], s[100:101]
	v_readlane_b32 s100, v0, 50
	v_readlane_b32 s101, v0, 51
	s_nop 1
	v_pk_mul_f32 v[132:133], v[132:133], s[100:101]
	v_readlane_b32 s100, v0, 54
	v_readlane_b32 s101, v0, 55
	s_nop 1
	v_pk_mul_f32 v[136:137], v[136:137], s[100:101]
	v_readlane_b32 s100, v0, 58
	v_readlane_b32 s101, v0, 59
	s_nop 1
	v_pk_mul_f32 v[140:141], v[140:141], s[100:101]
	v_readlane_b32 s100, v0, 62
	v_readlane_b32 s101, v0, 63
	s_nop 1
	v_pk_mul_f32 v[156:157], v[156:157], s[100:101]

.LBB0_805:
	s_cmp_eq_u64 s[68:69], 0
	s_cbranch_scc1 .LBB0_807
	s_mov_b32 s53, s41
	s_lshl_b64 s[72:73], s[52:53], 2
	s_add_u32 s68, s68, s72
	s_addc_u32 s69, s69, s73
	s_mov_b64 s[100:101], exec
	s_mov_b64 exec, -1
	v_mbcnt_lo_u32_b32 v90, -1, 0
	v_mbcnt_hi_u32_b32 v90, -1, v90
	v_lshlrev_b32_e32 v90, 2, v90
	global_load_dword v90, v90, s[68:69]
	s_mov_b64 exec, s[100:101]
	s_waitcnt vmcnt(0)
	v_readlane_b32 s100, v90, 12
	v_readlane_b32 s101, v90, 13
	s_nop 1
	v_pk_mul_f32 v[16:17], v[16:17], s[100:101]
	v_readlane_b32 s100, v90, 8
	v_readlane_b32 s101, v90, 9
	s_nop 1
	v_pk_mul_f32 v[12:13], v[12:13], s[100:101]
	v_readlane_b32 s100, v90, 4
	v_readlane_b32 s101, v90, 5
	s_nop 1
	v_pk_mul_f32 v[8:9], v[8:9], s[100:101]
	v_readlane_b32 s100, v90, 0
	v_readlane_b32 s101, v90, 1
	s_nop 1
	v_pk_mul_f32 v[4:5], v[4:5], s[100:101]
	v_readlane_b32 s100, v90, 2
	v_readlane_b32 s101, v90, 3
	s_nop 1
	v_pk_mul_f32 v[6:7], v[6:7], s[100:101]
	v_readlane_b32 s100, v90, 6
	v_readlane_b32 s101, v90, 7
	s_nop 1
	v_pk_mul_f32 v[10:11], v[10:11], s[100:101]
	v_readlane_b32 s100, v90, 10
	v_readlane_b32 s101, v90, 11
	s_nop 1
	v_pk_mul_f32 v[14:15], v[14:15], s[100:101]
	v_readlane_b32 s100, v90, 14
	v_readlane_b32 s101, v90, 15
	s_nop 1
	v_pk_mul_f32 v[18:19], v[18:19], s[100:101]
	v_readlane_b32 s100, v90, 28
	v_readlane_b32 s101, v90, 29
	s_nop 1
	v_pk_mul_f32 v[32:33], v[32:33], s[100:101]
	v_readlane_b32 s100, v90, 24
	v_readlane_b32 s101, v90, 25
	s_nop 1
	v_pk_mul_f32 v[28:29], v[28:29], s[100:101]
	v_readlane_b32 s100, v90, 20
	v_readlane_b32 s101, v90, 21
	s_nop 1
	v_pk_mul_f32 v[24:25], v[24:25], s[100:101]
	v_readlane_b32 s100, v90, 16
	v_readlane_b32 s101, v90, 17
	s_nop 1
	v_pk_mul_f32 v[20:21], v[20:21], s[100:101]
	v_readlane_b32 s100, v90, 18
	v_readlane_b32 s101, v90, 19
	s_nop 1
	v_pk_mul_f32 v[22:23], v[22:23], s[100:101]
	v_readlane_b32 s100, v90, 22
	v_readlane_b32 s101, v90, 23
	s_nop 1
	v_pk_mul_f32 v[26:27], v[26:27], s[100:101]
	v_readlane_b32 s100, v90, 26
	v_readlane_b32 s101, v90, 27
	s_nop 1
	v_pk_mul_f32 v[30:31], v[30:31], s[100:101]
	v_readlane_b32 s100, v90, 30
	v_readlane_b32 s101, v90, 31
	s_nop 1
	v_pk_mul_f32 v[34:35], v[34:35], s[100:101]
	v_readlane_b32 s100, v90, 44
	v_readlane_b32 s101, v90, 45
	s_nop 1
	v_pk_mul_f32 v[48:49], v[48:49], s[100:101]
	v_readlane_b32 s100, v90, 40
	v_readlane_b32 s101, v90, 41
	s_nop 1
	v_pk_mul_f32 v[44:45], v[44:45], s[100:101]
	v_readlane_b32 s100, v90, 36
	v_readlane_b32 s101, v90, 37
	s_nop 1
	v_pk_mul_f32 v[40:41], v[40:41], s[100:101]
	v_readlane_b32 s100, v90, 32
	v_readlane_b32 s101, v90, 33
	s_nop 1
	v_pk_mul_f32 v[36:37], v[36:37], s[100:101]
	v_readlane_b32 s100, v90, 34
	v_readlane_b32 s101, v90, 35
	s_nop 1
	v_pk_mul_f32 v[38:39], v[38:39], s[100:101]
	v_readlane_b32 s100, v90, 38
	v_readlane_b32 s101, v90, 39
	s_nop 1
	v_pk_mul_f32 v[42:43], v[42:43], s[100:101]
	v_readlane_b32 s100, v90, 42
	v_readlane_b32 s101, v90, 43
	s_nop 1
	v_pk_mul_f32 v[46:47], v[46:47], s[100:101]
	v_readlane_b32 s100, v90, 46
	v_readlane_b32 s101, v90, 47
	s_nop 1
	v_pk_mul_f32 v[50:51], v[50:51], s[100:101]
	v_readlane_b32 s100, v90, 60
	v_readlane_b32 s101, v90, 61
	s_nop 1
	v_pk_mul_f32 v[64:65], v[64:65], s[100:101]
	v_readlane_b32 s100, v90, 56
	v_readlane_b32 s101, v90, 57
	s_nop 1
	v_pk_mul_f32 v[60:61], v[60:61], s[100:101]
	v_readlane_b32 s100, v90, 52
	v_readlane_b32 s101, v90, 53
	s_nop 1
	v_pk_mul_f32 v[56:57], v[56:57], s[100:101]
	v_readlane_b32 s100, v90, 48
	v_readlane_b32 s101, v90, 49
	s_nop 1
	v_pk_mul_f32 v[52:53], v[52:53], s[100:101]
	v_readlane_b32 s100, v90, 50
	v_readlane_b32 s101, v90, 51
	s_nop 1
	v_pk_mul_f32 v[54:55], v[54:55], s[100:101]
	v_readlane_b32 s100, v90, 54
	v_readlane_b32 s101, v90, 55
	s_nop 1
	v_pk_mul_f32 v[58:59], v[58:59], s[100:101]
	v_readlane_b32 s100, v90, 58
	v_readlane_b32 s101, v90, 59
	s_nop 1
	v_pk_mul_f32 v[62:63], v[62:63], s[100:101]
	v_readlane_b32 s100, v90, 62
	v_readlane_b32 s101, v90, 63
	s_nop 1
	v_pk_mul_f32 v[66:67], v[66:67], s[100:101]

.LBB0_925:
	s_cmp_eq_u64 s[70:71], 0
	s_cbranch_scc1 .LBB0_927
	s_mov_b32 s79, s41
	s_lshl_b64 s[44:45], s[78:79], 2
	s_add_u32 s70, s70, s44
	s_addc_u32 s71, s71, s45
	s_mov_b64 s[100:101], exec
	s_mov_b64 exec, -1
	v_mbcnt_lo_u32_b32 v0, -1, 0
	v_mbcnt_hi_u32_b32 v0, -1, v0
	v_lshlrev_b32_e32 v0, 2, v0
	global_load_dword v0, v0, s[70:71]
	s_mov_b64 exec, s[100:101]
	s_waitcnt vmcnt(0)
	v_readlane_b32 s100, v0, 12
	v_readlane_b32 s101, v0, 13
	s_nop 1
	v_pk_mul_f32 v[94:95], v[94:95], s[100:101]
	v_readlane_b32 s100, v0, 8
	v_readlane_b32 s101, v0, 9
	s_nop 1
	v_pk_mul_f32 v[90:91], v[90:91], s[100:101]
	v_readlane_b32 s100, v0, 4
	v_readlane_b32 s101, v0, 5
	s_nop 1
	v_pk_mul_f32 v[86:87], v[86:87], s[100:101]
	v_readlane_b32 s100, v0, 0
	v_readlane_b32 s101, v0, 1
	s_nop 1
	v_pk_mul_f32 v[82:83], v[82:83], s[100:101]
	v_readlane_b32 s100, v0, 2
	v_readlane_b32 s101, v0, 3
	s_nop 1
	v_pk_mul_f32 v[84:85], v[84:85], s[100:101]
	v_readlane_b32 s100, v0, 6
	v_readlane_b32 s101, v0, 7
	s_nop 1
	v_pk_mul_f32 v[88:89], v[88:89], s[100:101]
	v_readlane_b32 s100, v0, 10
	v_readlane_b32 s101, v0, 11
	s_nop 1
	v_pk_mul_f32 v[92:93], v[92:93], s[100:101]
	v_readlane_b32 s100, v0, 14
	v_readlane_b32 s101, v0, 15
	s_nop 1
	v_pk_mul_f32 v[96:97], v[96:97], s[100:101]
	v_readlane_b32 s100, v0, 28
	v_readlane_b32 s101, v0, 29
	s_nop 1
	v_pk_mul_f32 v[110:111], v[110:111], s[100:101]
	v_readlane_b32 s100, v0, 24
	v_readlane_b32 s101, v0, 25
	s_nop 1
	v_pk_mul_f32 v[106:107], v[106:107], s[100:101]
	v_readlane_b32 s100, v0, 20
	v_readlane_b32 s101, v0, 21
	s_nop 1
	v_pk_mul_f32 v[102:103], v[102:103], s[100:101]
	v_readlane_b32 s100, v0, 16
	v_readlane_b32 s101, v0, 17
	s_nop 1
	v_pk_mul_f32 v[98:99], v[98:99], s[100:101]
	v_readlane_b32 s100, v0, 18
	v_readlane_b32 s101, v0, 19
	s_nop 1
	v_pk_mul_f32 v[100:101], v[100:101], s[100:101]
	v_readlane_b32 s100, v0, 22
	v_readlane_b32 s101, v0, 23
	s_nop 1
	v_pk_mul_f32 v[104:105], v[104:105], s[100:101]
	v_readlane_b32 s100, v0, 26
	v_readlane_b32 s101, v0, 27
	s_nop 1
	v_pk_mul_f32 v[108:109], v[108:109], s[100:101]
	v_readlane_b32 s100, v0, 30
	v_readlane_b32 s101, v0, 31
	s_nop 1
	v_pk_mul_f32 v[112:113], v[112:113], s[100:101]
	v_readlane_b32 s100, v0, 44
	v_readlane_b32 s101, v0, 45
	s_nop 1
	v_pk_mul_f32 v[126:127], v[126:127], s[100:101]
	v_readlane_b32 s100, v0, 40
	v_readlane_b32 s101, v0, 41
	s_nop 1
	v_pk_mul_f32 v[122:123], v[122:123], s[100:101]
	v_readlane_b32 s100, v0, 36
	v_readlane_b32 s101, v0, 37
	s_nop 1
	v_pk_mul_f32 v[118:119], v[118:119], s[100:101]
	v_readlane_b32 s100, v0, 32
	v_readlane_b32 s101, v0, 33
	s_nop 1
	v_pk_mul_f32 v[114:115], v[114:115], s[100:101]
	v_readlane_b32 s100, v0, 34
	v_readlane_b32 s101, v0, 35
	s_nop 1
	v_pk_mul_f32 v[116:117], v[116:117], s[100:101]
	v_readlane_b32 s100, v0, 38
	v_readlane_b32 s101, v0, 39
	s_nop 1
	v_pk_mul_f32 v[120:121], v[120:121], s[100:101]
	v_readlane_b32 s100, v0, 42
	v_readlane_b32 s101, v0, 43
	s_nop 1
	v_pk_mul_f32 v[124:125], v[124:125], s[100:101]
	v_readlane_b32 s100, v0, 46
	v_readlane_b32 s101, v0, 47
	s_nop 1
	v_pk_mul_f32 v[128:129], v[128:129], s[100:101]
	v_readlane_b32 s100, v0, 60
	v_readlane_b32 s101, v0, 61
	s_nop 1
	v_pk_mul_f32 v[142:143], v[142:143], s[100:101]
	v_readlane_b32 s100, v0, 56
	v_readlane_b32 s101, v0, 57
	s_nop 1
	v_pk_mul_f32 v[138:139], v[138:139], s[100:101]
	v_readlane_b32 s100, v0, 52
	v_readlane_b32 s101, v0, 53
	s_nop 1
	v_pk_mul_f32 v[134:135], v[134:135], s[100:101]
	v_readlane_b32 s100, v0, 48
	v_readlane_b32 s101, v0, 49
	s_nop 1
	v_pk_mul_f32 v[130:131], v[130:131], s[100:101]
	v_readlane_b32 s100, v0, 50
	v_readlane_b32 s101, v0, 51
	s_nop 1
	v_pk_mul_f32 v[132:133], v[132:133], s[100:101]
	v_readlane_b32 s100, v0, 54
	v_readlane_b32 s101, v0, 55
	s_nop 1
	v_pk_mul_f32 v[136:137], v[136:137], s[100:101]
	v_readlane_b32 s100, v0, 58
	v_readlane_b32 s101, v0, 59
	s_nop 1
	v_pk_mul_f32 v[140:141], v[140:141], s[100:101]
	v_readlane_b32 s100, v0, 62
	v_readlane_b32 s101, v0, 63
	s_nop 1
	v_pk_mul_f32 v[156:157], v[156:157], s[100:101]

.LBB0_974:
	s_cmp_eq_u64 s[46:47], 0
	s_cbranch_scc1 .LBB0_976
	s_mov_b32 s43, s41
	s_lshl_b64 s[68:69], s[42:43], 2
	s_add_u32 s46, s46, s68
	s_addc_u32 s47, s47, s69
	s_mov_b64 s[100:101], exec
	s_mov_b64 exec, -1
	v_mbcnt_lo_u32_b32 v90, -1, 0
	v_mbcnt_hi_u32_b32 v90, -1, v90
	v_lshlrev_b32_e32 v90, 2, v90
	global_load_dword v90, v90, s[46:47]
	s_mov_b64 exec, s[100:101]
	s_waitcnt vmcnt(0)
	v_readlane_b32 s100, v90, 12
	v_readlane_b32 s101, v90, 13
	s_nop 1
	v_pk_mul_f32 v[16:17], v[16:17], s[100:101]
	v_readlane_b32 s100, v90, 8
	v_readlane_b32 s101, v90, 9
	s_nop 1
	v_pk_mul_f32 v[12:13], v[12:13], s[100:101]
	v_readlane_b32 s100, v90, 4
	v_readlane_b32 s101, v90, 5
	s_nop 1
	v_pk_mul_f32 v[8:9], v[8:9], s[100:101]
	v_readlane_b32 s100, v90, 0
	v_readlane_b32 s101, v90, 1
	s_nop 1
	v_pk_mul_f32 v[4:5], v[4:5], s[100:101]
	v_readlane_b32 s100, v90, 2
	v_readlane_b32 s101, v90, 3
	s_nop 1
	v_pk_mul_f32 v[6:7], v[6:7], s[100:101]
	v_readlane_b32 s100, v90, 6
	v_readlane_b32 s101, v90, 7
	s_nop 1
	v_pk_mul_f32 v[10:11], v[10:11], s[100:101]
	v_readlane_b32 s100, v90, 10
	v_readlane_b32 s101, v90, 11
	s_nop 1
	v_pk_mul_f32 v[14:15], v[14:15], s[100:101]
	v_readlane_b32 s100, v90, 14
	v_readlane_b32 s101, v90, 15
	s_nop 1
	v_pk_mul_f32 v[18:19], v[18:19], s[100:101]
	v_readlane_b32 s100, v90, 28
	v_readlane_b32 s101, v90, 29
	s_nop 1
	v_pk_mul_f32 v[32:33], v[32:33], s[100:101]
	v_readlane_b32 s100, v90, 24
	v_readlane_b32 s101, v90, 25
	s_nop 1
	v_pk_mul_f32 v[28:29], v[28:29], s[100:101]
	v_readlane_b32 s100, v90, 20
	v_readlane_b32 s101, v90, 21
	s_nop 1
	v_pk_mul_f32 v[24:25], v[24:25], s[100:101]
	v_readlane_b32 s100, v90, 16
	v_readlane_b32 s101, v90, 17
	s_nop 1
	v_pk_mul_f32 v[20:21], v[20:21], s[100:101]
	v_readlane_b32 s100, v90, 18
	v_readlane_b32 s101, v90, 19
	s_nop 1
	v_pk_mul_f32 v[22:23], v[22:23], s[100:101]
	v_readlane_b32 s100, v90, 22
	v_readlane_b32 s101, v90, 23
	s_nop 1
	v_pk_mul_f32 v[26:27], v[26:27], s[100:101]
	v_readlane_b32 s100, v90, 26
	v_readlane_b32 s101, v90, 27
	s_nop 1
	v_pk_mul_f32 v[30:31], v[30:31], s[100:101]
	v_readlane_b32 s100, v90, 30
	v_readlane_b32 s101, v90, 31
	s_nop 1
	v_pk_mul_f32 v[34:35], v[34:35], s[100:101]
	v_readlane_b32 s100, v90, 44
	v_readlane_b32 s101, v90, 45
	s_nop 1
	v_pk_mul_f32 v[48:49], v[48:49], s[100:101]
	v_readlane_b32 s100, v90, 40
	v_readlane_b32 s101, v90, 41
	s_nop 1
	v_pk_mul_f32 v[44:45], v[44:45], s[100:101]
	v_readlane_b32 s100, v90, 36
	v_readlane_b32 s101, v90, 37
	s_nop 1
	v_pk_mul_f32 v[40:41], v[40:41], s[100:101]
	v_readlane_b32 s100, v90, 32
	v_readlane_b32 s101, v90, 33
	s_nop 1
	v_pk_mul_f32 v[36:37], v[36:37], s[100:101]
	v_readlane_b32 s100, v90, 34
	v_readlane_b32 s101, v90, 35
	s_nop 1
	v_pk_mul_f32 v[38:39], v[38:39], s[100:101]
	v_readlane_b32 s100, v90, 38
	v_readlane_b32 s101, v90, 39
	s_nop 1
	v_pk_mul_f32 v[42:43], v[42:43], s[100:101]
	v_readlane_b32 s100, v90, 42
	v_readlane_b32 s101, v90, 43
	s_nop 1
	v_pk_mul_f32 v[46:47], v[46:47], s[100:101]
	v_readlane_b32 s100, v90, 46
	v_readlane_b32 s101, v90, 47
	s_nop 1
	v_pk_mul_f32 v[50:51], v[50:51], s[100:101]
	v_readlane_b32 s100, v90, 60
	v_readlane_b32 s101, v90, 61
	s_nop 1
	v_pk_mul_f32 v[64:65], v[64:65], s[100:101]
	v_readlane_b32 s100, v90, 56
	v_readlane_b32 s101, v90, 57
	s_nop 1
	v_pk_mul_f32 v[60:61], v[60:61], s[100:101]
	v_readlane_b32 s100, v90, 52
	v_readlane_b32 s101, v90, 53
	s_nop 1
	v_pk_mul_f32 v[56:57], v[56:57], s[100:101]
	v_readlane_b32 s100, v90, 48
	v_readlane_b32 s101, v90, 49
	s_nop 1
	v_pk_mul_f32 v[52:53], v[52:53], s[100:101]
	v_readlane_b32 s100, v90, 50
	v_readlane_b32 s101, v90, 51
	s_nop 1
	v_pk_mul_f32 v[54:55], v[54:55], s[100:101]
	v_readlane_b32 s100, v90, 54
	v_readlane_b32 s101, v90, 55
	s_nop 1
	v_pk_mul_f32 v[58:59], v[58:59], s[100:101]
	v_readlane_b32 s100, v90, 58
	v_readlane_b32 s101, v90, 59
	s_nop 1
	v_pk_mul_f32 v[62:63], v[62:63], s[100:101]
	v_readlane_b32 s100, v90, 62
	v_readlane_b32 s101, v90, 63
	s_nop 1
	v_pk_mul_f32 v[66:67], v[66:67], s[100:101]

.LBB0_1372:
	s_cmp_eq_u64 s[12:13], 0
	s_cbranch_scc1 .LBB0_1374
	s_mov_b32 s11, s21
	s_lshl_b64 s[16:17], s[10:11], 2
	s_add_u32 s12, s12, s16
	s_addc_u32 s13, s13, s17
	s_mov_b64 s[100:101], exec
	s_mov_b64 exec, -1
	v_mbcnt_lo_u32_b32 v92, -1, 0
	v_mbcnt_hi_u32_b32 v92, -1, v92
	v_lshlrev_b32_e32 v92, 2, v92
	global_load_dword v92, v92, s[12:13]
	s_mov_b64 exec, s[100:101]
	s_waitcnt vmcnt(0)
	v_readlane_b32 s100, v92, 12
	v_readlane_b32 s101, v92, 13
	s_nop 1
	v_pk_mul_f32 v[18:19], v[18:19], s[100:101]
	v_readlane_b32 s100, v92, 8
	v_readlane_b32 s101, v92, 9
	s_nop 1
	v_pk_mul_f32 v[14:15], v[14:15], s[100:101]
	v_readlane_b32 s100, v92, 4
	v_readlane_b32 s101, v92, 5
	s_nop 1
	v_pk_mul_f32 v[10:11], v[10:11], s[100:101]
	v_readlane_b32 s100, v92, 0
	v_readlane_b32 s101, v92, 1
	s_nop 1
	v_pk_mul_f32 v[6:7], v[6:7], s[100:101]
	v_readlane_b32 s100, v92, 2
	v_readlane_b32 s101, v92, 3
	s_nop 1
	v_pk_mul_f32 v[8:9], v[8:9], s[100:101]
	v_readlane_b32 s100, v92, 6
	v_readlane_b32 s101, v92, 7
	s_nop 1
	v_pk_mul_f32 v[12:13], v[12:13], s[100:101]
	v_readlane_b32 s100, v92, 10
	v_readlane_b32 s101, v92, 11
	s_nop 1
	v_pk_mul_f32 v[16:17], v[16:17], s[100:101]
	v_readlane_b32 s100, v92, 14
	v_readlane_b32 s101, v92, 15
	s_nop 1
	v_pk_mul_f32 v[20:21], v[20:21], s[100:101]
	v_readlane_b32 s100, v92, 28
	v_readlane_b32 s101, v92, 29
	s_nop 1
	v_pk_mul_f32 v[34:35], v[34:35], s[100:101]
	v_readlane_b32 s100, v92, 24
	v_readlane_b32 s101, v92, 25
	s_nop 1
	v_pk_mul_f32 v[30:31], v[30:31], s[100:101]
	v_readlane_b32 s100, v92, 20
	v_readlane_b32 s101, v92, 21
	s_nop 1
	v_pk_mul_f32 v[26:27], v[26:27], s[100:101]
	v_readlane_b32 s100, v92, 16
	v_readlane_b32 s101, v92, 17
	s_nop 1
	v_pk_mul_f32 v[22:23], v[22:23], s[100:101]
	v_readlane_b32 s100, v92, 18
	v_readlane_b32 s101, v92, 19
	s_nop 1
	v_pk_mul_f32 v[24:25], v[24:25], s[100:101]
	v_readlane_b32 s100, v92, 22
	v_readlane_b32 s101, v92, 23
	s_nop 1
	v_pk_mul_f32 v[28:29], v[28:29], s[100:101]
	v_readlane_b32 s100, v92, 26
	v_readlane_b32 s101, v92, 27
	s_nop 1
	v_pk_mul_f32 v[32:33], v[32:33], s[100:101]
	v_readlane_b32 s100, v92, 30
	v_readlane_b32 s101, v92, 31
	s_nop 1
	v_pk_mul_f32 v[36:37], v[36:37], s[100:101]
	v_readlane_b32 s100, v92, 44
	v_readlane_b32 s101, v92, 45
	s_nop 1
	v_pk_mul_f32 v[50:51], v[50:51], s[100:101]
	v_readlane_b32 s100, v92, 40
	v_readlane_b32 s101, v92, 41
	s_nop 1
	v_pk_mul_f32 v[46:47], v[46:47], s[100:101]
	v_readlane_b32 s100, v92, 36
	v_readlane_b32 s101, v92, 37
	s_nop 1
	v_pk_mul_f32 v[42:43], v[42:43], s[100:101]
	v_readlane_b32 s100, v92, 32
	v_readlane_b32 s101, v92, 33
	s_nop 1
	v_pk_mul_f32 v[38:39], v[38:39], s[100:101]
	v_readlane_b32 s100, v92, 34
	v_readlane_b32 s101, v92, 35
	s_nop 1
	v_pk_mul_f32 v[40:41], v[40:41], s[100:101]
	v_readlane_b32 s100, v92, 38
	v_readlane_b32 s101, v92, 39
	s_nop 1
	v_pk_mul_f32 v[44:45], v[44:45], s[100:101]
	v_readlane_b32 s100, v92, 42
	v_readlane_b32 s101, v92, 43
	s_nop 1
	v_pk_mul_f32 v[48:49], v[48:49], s[100:101]
	v_readlane_b32 s100, v92, 46
	v_readlane_b32 s101, v92, 47
	s_nop 1
	v_pk_mul_f32 v[52:53], v[52:53], s[100:101]
	v_readlane_b32 s100, v92, 60
	v_readlane_b32 s101, v92, 61
	s_nop 1
	v_pk_mul_f32 v[66:67], v[66:67], s[100:101]
	v_readlane_b32 s100, v92, 56
	v_readlane_b32 s101, v92, 57
	s_nop 1
	v_pk_mul_f32 v[62:63], v[62:63], s[100:101]
	v_readlane_b32 s100, v92, 52
	v_readlane_b32 s101, v92, 53
	s_nop 1
	v_pk_mul_f32 v[58:59], v[58:59], s[100:101]
	v_readlane_b32 s100, v92, 48
	v_readlane_b32 s101, v92, 49
	s_nop 1
	v_pk_mul_f32 v[54:55], v[54:55], s[100:101]
	v_readlane_b32 s100, v92, 50
	v_readlane_b32 s101, v92, 51
	s_nop 1
	v_pk_mul_f32 v[56:57], v[56:57], s[100:101]
	v_readlane_b32 s100, v92, 54
	v_readlane_b32 s101, v92, 55
	s_nop 1
	v_pk_mul_f32 v[60:61], v[60:61], s[100:101]
	v_readlane_b32 s100, v92, 58
	v_readlane_b32 s101, v92, 59
	s_nop 1
	v_pk_mul_f32 v[64:65], v[64:65], s[100:101]
	v_readlane_b32 s100, v92, 62
	v_readlane_b32 s101, v92, 63
	s_nop 1
	v_pk_mul_f32 v[68:69], v[68:69], s[100:101]

.LBB0_1467:
	s_cmp_eq_u64 s[10:11], 0
	s_cbranch_scc1 .LBB0_1469
	s_mov_b32 s9, s21
	s_lshl_b64 s[14:15], s[8:9], 2
	s_add_u32 s10, s10, s14
	s_addc_u32 s11, s11, s15
	s_mov_b64 s[100:101], exec
	s_mov_b64 exec, -1
	v_mbcnt_lo_u32_b32 v92, -1, 0
	v_mbcnt_hi_u32_b32 v92, -1, v92
	v_lshlrev_b32_e32 v92, 2, v92
	global_load_dword v92, v92, s[10:11]
	s_mov_b64 exec, s[100:101]
	s_waitcnt vmcnt(0)
	v_readlane_b32 s100, v92, 12
	v_readlane_b32 s101, v92, 13
	s_nop 1
	v_pk_mul_f32 v[18:19], v[18:19], s[100:101]
	v_readlane_b32 s100, v92, 8
	v_readlane_b32 s101, v92, 9
	s_nop 1
	v_pk_mul_f32 v[14:15], v[14:15], s[100:101]
	v_readlane_b32 s100, v92, 4
	v_readlane_b32 s101, v92, 5
	s_nop 1
	v_pk_mul_f32 v[10:11], v[10:11], s[100:101]
	v_readlane_b32 s100, v92, 0
	v_readlane_b32 s101, v92, 1
	s_nop 1
	v_pk_mul_f32 v[6:7], v[6:7], s[100:101]
	v_readlane_b32 s100, v92, 2
	v_readlane_b32 s101, v92, 3
	s_nop 1
	v_pk_mul_f32 v[8:9], v[8:9], s[100:101]
	v_readlane_b32 s100, v92, 6
	v_readlane_b32 s101, v92, 7
	s_nop 1
	v_pk_mul_f32 v[12:13], v[12:13], s[100:101]
	v_readlane_b32 s100, v92, 10
	v_readlane_b32 s101, v92, 11
	s_nop 1
	v_pk_mul_f32 v[16:17], v[16:17], s[100:101]
	v_readlane_b32 s100, v92, 14
	v_readlane_b32 s101, v92, 15
	s_nop 1
	v_pk_mul_f32 v[20:21], v[20:21], s[100:101]
	v_readlane_b32 s100, v92, 28
	v_readlane_b32 s101, v92, 29
	s_nop 1
	v_pk_mul_f32 v[34:35], v[34:35], s[100:101]
	v_readlane_b32 s100, v92, 24
	v_readlane_b32 s101, v92, 25
	s_nop 1
	v_pk_mul_f32 v[30:31], v[30:31], s[100:101]
	v_readlane_b32 s100, v92, 20
	v_readlane_b32 s101, v92, 21
	s_nop 1
	v_pk_mul_f32 v[26:27], v[26:27], s[100:101]
	v_readlane_b32 s100, v92, 16
	v_readlane_b32 s101, v92, 17
	s_nop 1
	v_pk_mul_f32 v[22:23], v[22:23], s[100:101]
	v_readlane_b32 s100, v92, 18
	v_readlane_b32 s101, v92, 19
	s_nop 1
	v_pk_mul_f32 v[24:25], v[24:25], s[100:101]
	v_readlane_b32 s100, v92, 22
	v_readlane_b32 s101, v92, 23
	s_nop 1
	v_pk_mul_f32 v[28:29], v[28:29], s[100:101]
	v_readlane_b32 s100, v92, 26
	v_readlane_b32 s101, v92, 27
	s_nop 1
	v_pk_mul_f32 v[32:33], v[32:33], s[100:101]
	v_readlane_b32 s100, v92, 30
	v_readlane_b32 s101, v92, 31
	s_nop 1
	v_pk_mul_f32 v[36:37], v[36:37], s[100:101]
	v_readlane_b32 s100, v92, 44
	v_readlane_b32 s101, v92, 45
	s_nop 1
	v_pk_mul_f32 v[50:51], v[50:51], s[100:101]
	v_readlane_b32 s100, v92, 40
	v_readlane_b32 s101, v92, 41
	s_nop 1
	v_pk_mul_f32 v[46:47], v[46:47], s[100:101]
	v_readlane_b32 s100, v92, 36
	v_readlane_b32 s101, v92, 37
	s_nop 1
	v_pk_mul_f32 v[42:43], v[42:43], s[100:101]
	v_readlane_b32 s100, v92, 32
	v_readlane_b32 s101, v92, 33
	s_nop 1
	v_pk_mul_f32 v[38:39], v[38:39], s[100:101]
	v_readlane_b32 s100, v92, 34
	v_readlane_b32 s101, v92, 35
	s_nop 1
	v_pk_mul_f32 v[40:41], v[40:41], s[100:101]
	v_readlane_b32 s100, v92, 38
	v_readlane_b32 s101, v92, 39
	s_nop 1
	v_pk_mul_f32 v[44:45], v[44:45], s[100:101]
	v_readlane_b32 s100, v92, 42
	v_readlane_b32 s101, v92, 43
	s_nop 1
	v_pk_mul_f32 v[48:49], v[48:49], s[100:101]
	v_readlane_b32 s100, v92, 46
	v_readlane_b32 s101, v92, 47
	s_nop 1
	v_pk_mul_f32 v[52:53], v[52:53], s[100:101]
	v_readlane_b32 s100, v92, 60
	v_readlane_b32 s101, v92, 61
	s_nop 1
	v_pk_mul_f32 v[66:67], v[66:67], s[100:101]
	v_readlane_b32 s100, v92, 56
	v_readlane_b32 s101, v92, 57
	s_nop 1
	v_pk_mul_f32 v[62:63], v[62:63], s[100:101]
	v_readlane_b32 s100, v92, 52
	v_readlane_b32 s101, v92, 53
	s_nop 1
	v_pk_mul_f32 v[58:59], v[58:59], s[100:101]
	v_readlane_b32 s100, v92, 48
	v_readlane_b32 s101, v92, 49
	s_nop 1
	v_pk_mul_f32 v[54:55], v[54:55], s[100:101]
	v_readlane_b32 s100, v92, 50
	v_readlane_b32 s101, v92, 51
	s_nop 1
	v_pk_mul_f32 v[56:57], v[56:57], s[100:101]
	v_readlane_b32 s100, v92, 54
	v_readlane_b32 s101, v92, 55
	s_nop 1
	v_pk_mul_f32 v[60:61], v[60:61], s[100:101]
	v_readlane_b32 s100, v92, 58
	v_readlane_b32 s101, v92, 59
	s_nop 1
	v_pk_mul_f32 v[64:65], v[64:65], s[100:101]
	v_readlane_b32 s100, v92, 62
	v_readlane_b32 s101, v92, 63
	s_nop 1
	v_pk_mul_f32 v[68:69], v[68:69], s[100:101]

.LBB0_3086:
	s_cmp_eq_u64 s[14:15], 0
	s_cbranch_scc1 .LBB0_3088
	s_mov_b32 s13, s21
	s_lshl_b64 s[18:19], s[12:13], 2
	s_add_u32 s14, s14, s18
	s_addc_u32 s15, s15, s19
	s_mov_b64 s[100:101], exec
	s_mov_b64 exec, -1
	v_mbcnt_lo_u32_b32 v92, -1, 0
	v_mbcnt_hi_u32_b32 v92, -1, v92
	v_lshlrev_b32_e32 v92, 2, v92
	global_load_dword v92, v92, s[14:15]
	s_mov_b64 exec, s[100:101]
	s_waitcnt vmcnt(0)
	v_readlane_b32 s100, v92, 12
	v_readlane_b32 s101, v92, 13
	s_nop 1
	v_pk_mul_f32 v[18:19], v[18:19], s[100:101]
	v_readlane_b32 s100, v92, 8
	v_readlane_b32 s101, v92, 9
	s_nop 1
	v_pk_mul_f32 v[14:15], v[14:15], s[100:101]
	v_readlane_b32 s100, v92, 4
	v_readlane_b32 s101, v92, 5
	s_nop 1
	v_pk_mul_f32 v[10:11], v[10:11], s[100:101]
	v_readlane_b32 s100, v92, 0
	v_readlane_b32 s101, v92, 1
	s_nop 1
	v_pk_mul_f32 v[6:7], v[6:7], s[100:101]
	v_readlane_b32 s100, v92, 2
	v_readlane_b32 s101, v92, 3
	s_nop 1
	v_pk_mul_f32 v[8:9], v[8:9], s[100:101]
	v_readlane_b32 s100, v92, 6
	v_readlane_b32 s101, v92, 7
	s_nop 1
	v_pk_mul_f32 v[12:13], v[12:13], s[100:101]
	v_readlane_b32 s100, v92, 10
	v_readlane_b32 s101, v92, 11
	s_nop 1
	v_pk_mul_f32 v[16:17], v[16:17], s[100:101]
	v_readlane_b32 s100, v92, 14
	v_readlane_b32 s101, v92, 15
	s_nop 1
	v_pk_mul_f32 v[20:21], v[20:21], s[100:101]
	v_readlane_b32 s100, v92, 28
	v_readlane_b32 s101, v92, 29
	s_nop 1
	v_pk_mul_f32 v[34:35], v[34:35], s[100:101]
	v_readlane_b32 s100, v92, 24
	v_readlane_b32 s101, v92, 25
	s_nop 1
	v_pk_mul_f32 v[30:31], v[30:31], s[100:101]
	v_readlane_b32 s100, v92, 20
	v_readlane_b32 s101, v92, 21
	s_nop 1
	v_pk_mul_f32 v[26:27], v[26:27], s[100:101]
	v_readlane_b32 s100, v92, 16
	v_readlane_b32 s101, v92, 17
	s_nop 1
	v_pk_mul_f32 v[22:23], v[22:23], s[100:101]
	v_readlane_b32 s100, v92, 18
	v_readlane_b32 s101, v92, 19
	s_nop 1
	v_pk_mul_f32 v[24:25], v[24:25], s[100:101]
	v_readlane_b32 s100, v92, 22
	v_readlane_b32 s101, v92, 23
	s_nop 1
	v_pk_mul_f32 v[28:29], v[28:29], s[100:101]
	v_readlane_b32 s100, v92, 26
	v_readlane_b32 s101, v92, 27
	s_nop 1
	v_pk_mul_f32 v[32:33], v[32:33], s[100:101]
	v_readlane_b32 s100, v92, 30
	v_readlane_b32 s101, v92, 31
	s_nop 1
	v_pk_mul_f32 v[36:37], v[36:37], s[100:101]
	v_readlane_b32 s100, v92, 44
	v_readlane_b32 s101, v92, 45
	s_nop 1
	v_pk_mul_f32 v[50:51], v[50:51], s[100:101]
	v_readlane_b32 s100, v92, 40
	v_readlane_b32 s101, v92, 41
	s_nop 1
	v_pk_mul_f32 v[46:47], v[46:47], s[100:101]
	v_readlane_b32 s100, v92, 36
	v_readlane_b32 s101, v92, 37
	s_nop 1
	v_pk_mul_f32 v[42:43], v[42:43], s[100:101]
	v_readlane_b32 s100, v92, 32
	v_readlane_b32 s101, v92, 33
	s_nop 1
	v_pk_mul_f32 v[38:39], v[38:39], s[100:101]
	v_readlane_b32 s100, v92, 34
	v_readlane_b32 s101, v92, 35
	s_nop 1
	v_pk_mul_f32 v[40:41], v[40:41], s[100:101]
	v_readlane_b32 s100, v92, 38
	v_readlane_b32 s101, v92, 39
	s_nop 1
	v_pk_mul_f32 v[44:45], v[44:45], s[100:101]
	v_readlane_b32 s100, v92, 42
	v_readlane_b32 s101, v92, 43
	s_nop 1
	v_pk_mul_f32 v[48:49], v[48:49], s[100:101]
	v_readlane_b32 s100, v92, 46
	v_readlane_b32 s101, v92, 47
	s_nop 1
	v_pk_mul_f32 v[52:53], v[52:53], s[100:101]
	v_readlane_b32 s100, v92, 60
	v_readlane_b32 s101, v92, 61
	s_nop 1
	v_pk_mul_f32 v[66:67], v[66:67], s[100:101]
	v_readlane_b32 s100, v92, 56
	v_readlane_b32 s101, v92, 57
	s_nop 1
	v_pk_mul_f32 v[62:63], v[62:63], s[100:101]
	v_readlane_b32 s100, v92, 52
	v_readlane_b32 s101, v92, 53
	s_nop 1
	v_pk_mul_f32 v[58:59], v[58:59], s[100:101]
	v_readlane_b32 s100, v92, 48
	v_readlane_b32 s101, v92, 49
	s_nop 1
	v_pk_mul_f32 v[54:55], v[54:55], s[100:101]
	v_readlane_b32 s100, v92, 50
	v_readlane_b32 s101, v92, 51
	s_nop 1
	v_pk_mul_f32 v[56:57], v[56:57], s[100:101]
	v_readlane_b32 s100, v92, 54
	v_readlane_b32 s101, v92, 55
	s_nop 1
	v_pk_mul_f32 v[60:61], v[60:61], s[100:101]
	v_readlane_b32 s100, v92, 58
	v_readlane_b32 s101, v92, 59
	s_nop 1
	v_pk_mul_f32 v[64:65], v[64:65], s[100:101]
	v_readlane_b32 s100, v92, 62
	v_readlane_b32 s101, v92, 63
	s_nop 1
	v_pk_mul_f32 v[68:69], v[68:69], s[100:101]
